# layer-dependent P1b schedule (chain CUs 4 tiles; freed tiles to CUs 32-95 in layer 0, CUs 160-223 in layer 1); all layer-1 weight copies moved into layer 0 P1b
# speedup vs baseline: 1.0257x; 1.0257x over previous
;     __device__ __forceinline__ bool next(int i, Unit& u) const {
;     ...
;         else if (c >= 32) { if (i < 8) L = i * 224 + (c - 32); else if (i == 8 && c < 96) L = 1984 + (c - 32); else return false; }
.LBB0_416:
	s_and_b64 vcc, exec, s[26:27]
	s_cbranch_vccz .LBB0_421
	s_cmp_gt_u32 s2, 6
	s_mov_b64 s[26:27], -1
	s_cbranch_scc0 .LBB0_419
	s_cmp_eq_u32 s40, 8
	v_readlane_b32 s14, v254, 23
	s_cselect_b64 s[2:3], -1, 0
	v_readlane_b32 s15, v254, 24
	s_and_b64 s[14:15], s[14:15], s[2:3]
	s_mov_b64 s[26:27], 0
	v_readlane_b32 s3, v254, 25
	v_readlane_b32 s2, v255, 35
	s_cmp_eq_u32 s2, 0
	s_cbranch_scc0 .Lsched_layer1
	s_cmp_eq_u32 s40, 9
	s_cbranch_scc0 .LBB0_421
	s_cmp_lt_u32 s69, 96
	s_cbranch_scc0 .LBB0_421
	s_add_i32 s3, s3, -64
	s_mov_b64 s[14:15], -1
	s_branch .LBB0_421
.Lsched_layer1:
	s_cmp_eq_u32 s40, 8
	s_cbranch_scc0 .LBB0_421
	s_cmp_ge_u32 s69, 160
	s_cbranch_scc0 .LBB0_421
	s_cmp_lt_u32 s69, 224
	s_cbranch_scc0 .LBB0_421
	s_add_i32 s3, s3, -192
	s_mov_b64 s[14:15], -1
	s_branch .LBB0_421

; #define LAS __attribute__((address_space(3)))
; #define P (*({ CParams* q_ = kp; asm volatile("" : "+s"(q_)); q_; }))
; #define wave (__builtin_amdgcn_readfirstlane(tid >> 6))
;     unsigned char* ws = P.ws;
;     LAS float* scr = (LAS float*)(lds + wave * 16384);
;     constexpr int I_IN = (DM / 64) * (NPROJ / 32), I_OUT = (DM / 64) * (DM / 32), I_KV = (DM / 64) * (NKV / 32);
;     if (which & 1) p0_matrix(P.w_in + (size_t)l * DM * NPROJ, P.norm_g + l * DM, DM, NPROJ, (bf16_t*)(ws + WS_WIN) + (size_t)l * NPROJ * DM, scr, I_IN, gw, NGW, lane);
;     if (which & 2) p0_matrix(P.w_out + (size_t)l * DM * DM, nullptr, DM, DM, (bf16_t*)(ws + WS_WOUT) + (size_t)l * DM * DM, scr, I_OUT, gw, NGW, lane);
;     if (which & 4) p0_matrix(P.w_kv + (size_t)l * DM * NKV, P.mem_ng + l * DM, DM, NKV, (bf16_t*)(ws + WS_WKV) + (size_t)l * NKV * DM, scr, I_KV, gw, NGW, lane);
; __global__ void __launch_bounds__(NTHREADS, 2) fwd_megakernel(Params P_) {
;     ...
;         if (bx >= 160) { int t2 = threadIdx.x; asm volatile("" : "+v"(t2)); const int w2 = __builtin_amdgcn_readfirstlane(t2 >> 6);
;             convert_weights(P, 1, lds, (bx - 160) * NWAVES + w2, 96 * NWAVES, t2 & 63, w2, l == 0 ? 5 : 2); }
.LBB0_517:
	v_readlane_b32 s0, v254, 44
	v_readlane_b32 s1, v254, 45
	s_andn2_b64 vcc, exec, s[0:1]
	s_cbranch_vccnz .LBB0_693
	v_mov_b32_e32 v0, v218
	s_mov_b64 s[12:13], s[74:75]
	v_readfirstlane_b32 s0, v0
	s_ashr_i32 s2, s0, 6
	v_readlane_b32 s0, v254, 46
	s_add_i32 s6, s0, s2
	s_load_dwordx2 s[10:11], s[12:13], 0xa0
	s_and_b64 s[0:1], s[94:95], exec
	s_cselect_b32 s1, 7, 0
	s_lshl_b32 s0, s2, 14
	s_add_i32 s0, s0, 0
	s_bitcmp0_b32 s1, 0
	v_and_b32_e32 v140, 63, v0
	s_cbranch_scc1 .LBB0_598
	s_cmpk_gt_i32 s6, 0x5fff
	s_cbranch_scc1 .LBB0_598
	s_load_dwordx4 s[20:23], s[12:13], 0x18
	v_lshlrev_b32_e32 v0, 4, v140
	v_and_b32_e32 v196, 0x70, v0
	s_mov_b64 s[2:3], 0xc000000
	v_lshrrev_b32_e32 v141, 3, v140
	s_waitcnt lgkmcnt(0)
	v_lshl_add_u64 v[0:1], s[22:23], 0, v[196:197]
	v_lshl_add_u64 v[132:133], v[0:1], 0, s[2:3]
	v_lshlrev_b32_e32 v0, 3, v140
	v_and_b32_e32 v0, 56, v0
	s_add_u32 s14, s20, 0x4000
	v_add_u32_e32 v2, s0, v196
	s_movk_i32 s2, 0x84
	v_lshlrev_b32_e32 v196, 1, v0
	s_addc_u32 s15, s21, 0
	v_mad_u32_u24 v4, v141, s2, v227
	v_mul_u32_u24_e32 v5, 0x84, v0
	v_lshl_add_u64 v[0:1], s[10:11], 0, v[196:197]
	s_mov_b64 s[2:3], 0x6200000
	s_cmp_lg_u64 s[20:21], 0
	v_mul_u32_u24_e32 v3, 0x84, v141
	v_lshl_add_u64 v[134:135], v[0:1], 0, s[2:3]
	v_lshlrev_b32_e32 v0, 2, v141
	s_cselect_b64 s[18:19], -1, 0
	v_or_b32_e32 v142, 8, v141
	v_or_b32_e32 v143, 16, v141
	v_or_b32_e32 v144, 24, v141
	v_or_b32_e32 v145, 32, v141
	v_or_b32_e32 v146, 40, v141
	v_or_b32_e32 v147, 48, v141
	v_or_b32_e32 v148, 56, v141
	v_add3_u32 v149, s0, v5, v0
	s_lshl_b32 s2, s6, 5
	v_add_u32_e32 v150, v2, v3
	v_add_u32_e32 v151, v2, v4
	s_mov_b32 s3, s6
	s_branch .LBB0_523
